# sliding-window attention: bias LDS reads batched, V fragment reads hoisted; forgetting attention diagonal path F reads batched
# speedup vs baseline: 1.0026x; 1.0026x over previous
; template <int MODE>
; DI void attn_item(const CP& p, int l, int b, int head, int qt, char* smem) {
;     ...
;         if (__builtin_amdgcn_readfirstlane((int)need_mask)) { FX_INIT(true) } else { FX_INIT(false) }
.Lfx_masked:
	ds_read_b128 v[216:219], v1 offset:36864
	ds_read_b128 v[220:223], v1 offset:36896
	ds_read_b128 v[224:227], v1 offset:36928
	ds_read_b128 v[228:231], v1 offset:36960
	ds_read_b128 v[232:235], v1 offset:36992
	ds_read_b128 v[236:239], v1 offset:37024
	ds_read_b128 v[240:243], v1 offset:37056
	ds_read_b128 v[244:247], v1 offset:37088
	s_waitcnt lgkmcnt(0)
	ds_read_b128 v[114:117], v195 offset:4608
	ds_read_b128 v[118:121], v195 offset:4640
	ds_read_b128 v[122:125], v195 offset:4672
	ds_read_b128 v[126:129], v195 offset:4704
	v_or_b32_e32 v2, v174, v187
	v_cmp_le_i32_e32 vcc, v2, v168
	v_sub_f32_e32 v3, v0, v216
	s_nop 0
	v_cndmask_b32_e32 v66, v214, v3, vcc
	v_sub_f32_e32 v3, v0, v217
	v_cmp_lt_i32_e32 vcc, v2, v168
	v_pk_add_f32 v[4:5], v[0:1], v[218:219] op_sel_hi:[0,1] neg_lo:[0,1] neg_hi:[0,1]
	v_or_b32_e32 v6, 2, v2
	v_cndmask_b32_e32 v67, v214, v3, vcc
	v_or_b32_e32 v3, 3, v2
	v_cmp_le_i32_e32 vcc, v6, v168
	v_or_b32_e32 v6, 8, v2
	s_nop 0
	v_cndmask_b32_e32 v68, v214, v4, vcc
	v_cmp_le_i32_e32 vcc, v3, v167
	v_or_b32_e32 v3, 9, v2
	s_nop 0
	v_cndmask_b32_e32 v69, v214, v5, vcc
	v_pk_add_f32 v[4:5], v[0:1], v[220:221] op_sel_hi:[0,1] neg_lo:[0,1] neg_hi:[0,1]
	v_cmp_le_i32_e32 vcc, v6, v168
	v_or_b32_e32 v6, 10, v2
	v_or_b32_e32 v8, 16, v2
	v_cndmask_b32_e32 v70, v214, v4, vcc
	v_cmp_le_i32_e32 vcc, v3, v167
	v_or_b32_e32 v3, 11, v2
	s_nop 0
	v_cndmask_b32_e32 v71, v214, v5, vcc
	v_pk_add_f32 v[4:5], v[0:1], v[222:223] op_sel_hi:[0,1] neg_lo:[0,1] neg_hi:[0,1]
	v_cmp_le_i32_e32 vcc, v6, v168
	s_nop 1
	v_cndmask_b32_e32 v72, v214, v4, vcc
	v_cmp_le_i32_e32 vcc, v3, v167
	v_or_b32_e32 v3, 17, v2
	s_nop 0
	v_cndmask_b32_e32 v73, v214, v5, vcc
	v_cmp_le_i32_e32 vcc, v8, v168
	v_or_b32_e32 v8, 24, v2
	v_pk_add_f32 v[4:5], v[0:1], v[224:225] op_sel_hi:[0,1] neg_lo:[0,1] neg_hi:[0,1]
	v_cndmask_b32_e32 v74, v214, v4, vcc
	v_cmp_le_i32_e32 vcc, v3, v167
	v_or_b32_e32 v3, 19, v2
	s_nop 0
	v_cndmask_b32_e32 v75, v214, v5, vcc
	v_pk_add_f32 v[4:5], v[0:1], v[226:227] op_sel_hi:[0,1] neg_lo:[0,1] neg_hi:[0,1]
	v_or_b32_e32 v6, 18, v2
	v_cmp_le_i32_e32 vcc, v6, v168
	s_nop 1
	v_cndmask_b32_e32 v76, v214, v4, vcc
	v_cmp_le_i32_e32 vcc, v3, v167
	v_or_b32_e32 v3, 25, v2
	s_nop 0
	v_cndmask_b32_e32 v77, v214, v5, vcc
	v_cmp_le_i32_e32 vcc, v8, v168
	v_or_b32_e32 v8, 32, v2
	v_pk_add_f32 v[4:5], v[0:1], v[228:229] op_sel_hi:[0,1] neg_lo:[0,1] neg_hi:[0,1]
	v_cndmask_b32_e32 v78, v214, v4, vcc
	v_cmp_le_i32_e32 vcc, v3, v167
	v_or_b32_e32 v3, 27, v2
	s_nop 0
	v_cndmask_b32_e32 v79, v214, v5, vcc
	v_pk_add_f32 v[4:5], v[0:1], v[230:231] op_sel_hi:[0,1] neg_lo:[0,1] neg_hi:[0,1]
	v_or_b32_e32 v6, 26, v2
	v_cmp_le_i32_e32 vcc, v6, v168
	s_nop 1
	v_cndmask_b32_e32 v80, v214, v4, vcc
	v_cmp_le_i32_e32 vcc, v3, v167
	v_or_b32_e32 v3, 33, v2
	s_nop 0
	v_cndmask_b32_e32 v81, v214, v5, vcc
	v_cmp_le_i32_e32 vcc, v8, v168
	v_or_b32_e32 v8, 40, v2
	v_pk_add_f32 v[4:5], v[0:1], v[232:233] op_sel_hi:[0,1] neg_lo:[0,1] neg_hi:[0,1]
	v_cndmask_b32_e32 v82, v214, v4, vcc
	v_cmp_le_i32_e32 vcc, v3, v167
	v_or_b32_e32 v3, 35, v2
	s_nop 0
	v_cndmask_b32_e32 v83, v214, v5, vcc
	v_pk_add_f32 v[4:5], v[0:1], v[234:235] op_sel_hi:[0,1] neg_lo:[0,1] neg_hi:[0,1]
	v_or_b32_e32 v6, 34, v2
	v_cmp_le_i32_e32 vcc, v6, v168
	s_nop 1
	v_cndmask_b32_e32 v84, v214, v4, vcc
	v_cmp_le_i32_e32 vcc, v3, v167
	v_or_b32_e32 v3, 41, v2
	s_nop 0
	v_cndmask_b32_e32 v85, v214, v5, vcc
	v_cmp_le_i32_e32 vcc, v8, v168
	v_or_b32_e32 v8, 48, v2
	v_pk_add_f32 v[4:5], v[0:1], v[236:237] op_sel_hi:[0,1] neg_lo:[0,1] neg_hi:[0,1]
	v_cndmask_b32_e32 v86, v214, v4, vcc
	v_cmp_le_i32_e32 vcc, v3, v167
	v_or_b32_e32 v3, 43, v2
	s_nop 0
	v_cndmask_b32_e32 v87, v214, v5, vcc
	v_pk_add_f32 v[4:5], v[0:1], v[238:239] op_sel_hi:[0,1] neg_lo:[0,1] neg_hi:[0,1]
	v_or_b32_e32 v6, 42, v2
	v_cmp_le_i32_e32 vcc, v6, v168
	s_nop 1
	v_cndmask_b32_e32 v88, v214, v4, vcc
	v_cmp_le_i32_e32 vcc, v3, v167
	v_or_b32_e32 v3, 49, v2
	s_nop 0
	v_cndmask_b32_e32 v89, v214, v5, vcc
	v_cmp_le_i32_e32 vcc, v8, v168
	v_pk_add_f32 v[4:5], v[0:1], v[240:241] op_sel_hi:[0,1] neg_lo:[0,1] neg_hi:[0,1]
	s_nop 0
	v_cndmask_b32_e32 v90, v214, v4, vcc
	v_cmp_le_i32_e32 vcc, v3, v167
	v_or_b32_e32 v3, 51, v2
	s_nop 0
	v_cndmask_b32_e32 v91, v214, v5, vcc
	v_pk_add_f32 v[4:5], v[0:1], v[242:243] op_sel_hi:[0,1] neg_lo:[0,1] neg_hi:[0,1]
	v_or_b32_e32 v6, 50, v2
	v_cmp_le_i32_e32 vcc, v6, v168
	s_nop 1
	v_cndmask_b32_e32 v92, v214, v4, vcc
	v_cmp_le_i32_e32 vcc, v3, v167
	v_or_b32_e32 v3, 56, v2
	s_nop 0
	v_cndmask_b32_e32 v93, v214, v5, vcc
	v_cmp_le_i32_e32 vcc, v3, v168
	v_or_b32_e32 v3, 59, v2
	v_pk_add_f32 v[4:5], v[0:1], v[244:245] op_sel_hi:[0,1] neg_lo:[0,1] neg_hi:[0,1]
	v_or_b32_e32 v1, 57, v2
	v_cndmask_b32_e32 v94, v214, v4, vcc
	v_cmp_le_i32_e32 vcc, v1, v167
	v_or_b32_e32 v2, 58, v2
	v_pk_add_f32 v[0:1], v[0:1], v[246:247] op_sel_hi:[0,1] neg_lo:[0,1] neg_hi:[0,1]
	v_cndmask_b32_e32 v95, v214, v5, vcc
	v_cmp_le_i32_e32 vcc, v2, v168
	s_nop 1
	v_cndmask_b32_e32 v96, v214, v0, vcc
	v_cmp_le_i32_e32 vcc, v3, v167
	s_nop 1
	v_cndmask_b32_e32 v97, v214, v1, vcc

; #define MFMA32(a, b, c) __builtin_amdgcn_mfma_f32_32x32x16_bf16((a), (b), (c), 0, 0, 0)
; DI float shx32(float v) { return shx(v, get_tid() & 63, 32); }
; template <int MODE>
; DI void attn_item(const CP& p, int l, int b, int head, int qt, char* smem) {
;     ...
; #pragma unroll
;       for (int rb = 0; rb < 2; ++rb)
; #pragma unroll
;         for (int ks = 0; ks < 4; ++ks) {
;           bf16x8 a = *(const bf16x8*)(cK + (rb * 32 + l32) * 72 + ks * 16 + hh * 8);
;           s[rb] = MFMA32(a, qf[ks], s[rb]);
;         }
;     ...
;         float mx = -INFINITY;
; #pragma unroll
;         for (int rb = 0; rb < 2; ++rb)
; #pragma unroll
;           for (int blk = 0; blk < 4; ++blk) {
; #pragma unroll
;             for (int e = 0; e < 4; ++e) {
;               const int r = 4 * blk + e;
;               const int dist = qrow - (kbase + 32 * rb + 8 * blk + e);
;               const float z2 = s[rb][r] + sBias[dist + 128];
;               s[rb][r] = z2;
;               mx = fmaxf(mx, z2);
;             }
;           }
;         mx = fmaxf(mx, shx32(mx));
.LBB0_429:
	s_add_i32 s4, s48, 64
	v_cmp_le_i32_e32 vcc, s4, v100
	s_add_i32 s4, s48, 0x7f
	v_cmp_ge_i32_e64 s[4:5], s4, v101
	s_and_b64 s[38:39], vcc, s[4:5]
	s_and_saveexec_b64 s[4:5], s[38:39]
	s_cbranch_execz .LBB0_431
	s_mul_i32 s38, s17, 0x2400
	v_add_u32_e32 v107, s38, v103
	ds_read_b128 v[34:37], v107
	ds_read_b128 v[38:41], v107 offset:32
	s_waitcnt lgkmcnt(1)
	v_mfma_f32_32x32x16_bf16 v[50:65], v[34:37], v[66:69], 0
	ds_read_b128 v[34:37], v107 offset:64
	ds_read_b128 v[108:111], v107 offset:4640
	s_waitcnt lgkmcnt(2)
	v_mfma_f32_32x32x16_bf16 v[50:65], v[38:41], v[70:73], v[50:65]
	s_waitcnt lgkmcnt(1)
	v_mfma_f32_32x32x16_bf16 v[50:65], v[34:37], v[74:77], v[50:65]
	ds_read_b128 v[34:37], v107 offset:96
	s_waitcnt lgkmcnt(0)
	v_mfma_f32_32x32x16_bf16 v[50:65], v[34:37], v[78:81], v[50:65]
	ds_read_b128 v[34:37], v107 offset:4608
	s_waitcnt lgkmcnt(0)
	v_mfma_f32_32x32x16_bf16 v[34:49], v[34:37], v[66:69], 0
	v_mfma_f32_32x32x16_bf16 v[34:49], v[108:111], v[70:73], v[34:49]
	ds_read_b128 v[108:111], v107 offset:4672
	s_waitcnt lgkmcnt(0)
	v_mfma_f32_32x32x16_bf16 v[34:49], v[108:111], v[74:77], v[34:49]
	ds_read_b128 v[108:111], v107 offset:4704
	v_add3_u32 v107, v32, s48, 64
	s_waitcnt lgkmcnt(0)
	v_mfma_f32_32x32x16_bf16 v[34:49], v[108:111], v[78:81], v[34:49]
	ds_read_b32 v216, v105 offset:236
	v_xor_b32_e32 v248, 0x3fffffc4, v107
	v_lshl_add_u32 v248, v248, 2, v102
	ds_read_b32 v218, v248 offset:38124
	ds_read2_b32 v[220:221], v105 offset0:56 offset1:57
	ds_read2_b32 v[222:223], v105 offset0:50 offset1:51
	ds_read2_b32 v[224:225], v105 offset0:48 offset1:49
	ds_read2_b32 v[226:227], v105 offset0:42 offset1:43
	ds_read2_b32 v[228:229], v105 offset0:40 offset1:41
	ds_read2_b32 v[230:231], v105 offset0:34 offset1:35
	ds_read2_b32 v[232:233], v105 offset0:32 offset1:33
	ds_read2_b32 v[234:235], v105 offset0:26 offset1:27
	ds_read2_b32 v[236:237], v105 offset0:24 offset1:25
	ds_read2_b32 v[238:239], v105 offset0:18 offset1:19
	ds_read2_b32 v[240:241], v105 offset0:16 offset1:17
	ds_read2_b32 v[242:243], v105 offset0:10 offset1:11
	ds_read2_b32 v[244:245], v105 offset0:8 offset1:9
	s_waitcnt lgkmcnt(6)
	v_add_f32_e32 v108, v50, v216
	v_add_f32_e32 v107, v51, v218
	v_max3_f32 v109, v108, s96, v107
	v_add_f32_e32 v52, v52, v221
	v_add_f32_e32 v53, v53, v220
	v_max3_f32 v109, v109, v52, v53
	v_add_f32_e32 v54, v54, v223
	v_add_f32_e32 v55, v55, v222
	v_max3_f32 v109, v109, v54, v55
	v_add_f32_e32 v56, v56, v225
	v_add_f32_e32 v57, v57, v224
	v_max3_f32 v109, v109, v56, v57
	v_add_f32_e32 v58, v58, v227
	v_add_f32_e32 v59, v59, v226
	v_max3_f32 v109, v109, v58, v59
	v_add_f32_e32 v60, v60, v229
	v_add_f32_e32 v61, v61, v228
	v_max3_f32 v109, v109, v60, v61
	v_add_f32_e32 v62, v62, v231
	v_add_f32_e32 v63, v63, v230
	v_max3_f32 v109, v109, v62, v63
	v_add_f32_e32 v64, v64, v233
	v_add_f32_e32 v65, v65, v232
	ds_read2_b32 v[246:247], v105 offset0:2 offset1:3
	ds_read2_b32 v[248:249], v105 offset1:1
	s_waitcnt lgkmcnt(0)
	v_add_u32_e32 v250, s38, v104
	v_add_u32_e32 v250, 0x4800, v250
	v_add_u32_e32 v251, 0x1000, v250
	ds_read2_b64 v[180:183], v250 offset1:2
	ds_read2_b64 v[184:187], v250 offset0:4 offset1:6
	ds_read2_b64 v[188:191], v250 offset0:8 offset1:10
	ds_read2_b64 v[192:195], v250 offset0:12 offset1:14
	ds_read2_b64 v[196:199], v251 offset0:64 offset1:66
	ds_read2_b64 v[216:219], v251 offset0:68 offset1:70
	ds_read2_b64 v[220:223], v251 offset0:72 offset1:74
	ds_read2_b64 v[224:227], v251 offset0:76 offset1:78
	v_max3_f32 v109, v109, v64, v65
	v_add_f32_e32 v110, v34, v235
	v_add_f32_e32 v50, v35, v234
	v_max3_f32 v51, v109, v110, v50
	v_add_f32_e32 v36, v36, v237
	v_add_f32_e32 v37, v37, v236
	v_max3_f32 v51, v51, v36, v37
	v_add_f32_e32 v38, v38, v239
	v_add_f32_e32 v39, v39, v238
	v_max3_f32 v51, v51, v38, v39
	v_add_f32_e32 v40, v40, v241
	v_add_f32_e32 v41, v41, v240
	v_max3_f32 v51, v51, v40, v41
	v_add_f32_e32 v42, v42, v243
	v_add_f32_e32 v43, v43, v242
	v_max3_f32 v51, v51, v42, v43
	v_add_f32_e32 v44, v44, v245
	v_add_f32_e32 v45, v45, v244
	v_max3_f32 v51, v51, v44, v45
	v_add_f32_e32 v46, v46, v247
	v_add_f32_e32 v47, v47, v246
	v_max3_f32 v51, v51, v46, v47
	v_add_f32_e32 v34, v49, v248
	v_mov_b32_e32 v49, v202
	v_add_f32_e32 v35, v48, v249
	v_lshlrev_b32_e32 v49, 2, v49
	v_max3_f32 v48, v51, v35, v34
	v_bitop3_b32 v49, v49, s84, v211 bitop3:0x6c
	ds_bpermute_b32 v49, v49, v48
	s_waitcnt lgkmcnt(0)
; #define MFMA32(a, b, c) __builtin_amdgcn_mfma_f32_32x32x16_bf16((a), (b), (c), 0, 0, 0)
; DI unsigned pk2(float a, float b) { f2_t v = {a, b}; bf2_t r = __builtin_convertvector(v, bf2_t); return __builtin_bit_cast(unsigned, r); }
; DI float ex2(float x) { return __builtin_amdgcn_exp2f(x); }
; DI float shx32(float v) { return shx(v, get_tid() & 63, 32); }
; template <int MODE>
; DI void attn_item(const CP& p, int l, int b, int head, int qt, char* smem) {
;     ...
;         const float mn = fmaxf(m, mx);
;         const float corr = ex2(m - mn);
;         m = mn;
;         float sum = 0.f;
; #pragma unroll
;         for (int rb = 0; rb < 2; ++rb)
; #pragma unroll
;           for (int r = 0; r < 16; ++r) {
;             const float e = ex2(s[rb][r] - mn);
;             s[rb][r] = e;
;             sum += e;
;           }
;         sum += shx32(sum);
;         lsum = lsum * corr + sum;
; #pragma unroll
;         for (int r = 0; r < 16; ++r) { o[0][r] *= corr; o[1][r] *= corr; }
;       }
;       bf16x8 pf[4];
; #pragma unroll
;       for (int j = 0; j < 4; ++j) {
;         const int rb = j >> 1, r0 = (j & 1) * 8;
;         u32x4 u;
;         u.x = pk2(s[rb][r0], s[rb][r0 + 1]);
;         u.y = pk2(s[rb][r0 + 2], s[rb][r0 + 3]);
;         u.z = pk2(s[rb][r0 + 4], s[rb][r0 + 5]);
;         u.w = pk2(s[rb][r0 + 6], s[rb][r0 + 7]);
;         pf[j] = __builtin_bit_cast(bf16x8, u);
;       }
; #pragma unroll
;       for (int db = 0; db < 2; ++db)
; #pragma unroll
;         for (int j = 0; j < 4; ++j) {
;           const u16* vp = cV + (db * 32 + l32) * 72 + 16 * j + 4 * hh;
;           u32x2 lo = *(const u32x2*)(vp);
;           u32x2 hi = *(const u32x2*)(vp + 8);
;           u32x4 u = {lo.x, lo.y, hi.x, hi.y};
;           o[db] = MFMA32(__builtin_bit_cast(bf16x8, u), pf[j], o[db]);
;         }
	v_max3_f32 v51, v106, v48, v49
	v_sub_f32_e32 v49, v108, v51
	v_exp_f32_e32 v49, v49
	v_sub_f32_e32 v107, v107, v51
	v_exp_f32_e32 v107, v107
	v_sub_f32_e32 v52, v52, v51
	v_exp_f32_e32 v108, v52
	v_sub_f32_e32 v53, v53, v51
	v_exp_f32_e32 v53, v53
	v_sub_f32_e32 v54, v54, v51
	v_sub_f32_e32 v48, v106, v51
	v_add_f32_e32 v106, 0, v49
	v_exp_f32_e32 v54, v54
	v_sub_f32_e32 v55, v55, v51
	v_add_f32_e32 v106, v107, v106
	v_exp_f32_e32 v55, v55
	v_sub_f32_e32 v56, v56, v51
	v_add_f32_e32 v52, v108, v106
	v_exp_f32_e32 v56, v56
	v_sub_f32_e32 v57, v57, v51
	v_add_f32_e32 v52, v53, v52
	v_exp_f32_e32 v57, v57
	v_sub_f32_e32 v58, v58, v51
	v_add_f32_e32 v52, v54, v52
	v_exp_f32_e32 v58, v58
	v_sub_f32_e32 v59, v59, v51
	v_add_f32_e32 v52, v55, v52
	v_exp_f32_e32 v59, v59
	v_sub_f32_e32 v60, v60, v51
	v_add_f32_e32 v52, v56, v52
	v_exp_f32_e32 v60, v60
	v_sub_f32_e32 v61, v61, v51
	v_add_f32_e32 v52, v57, v52
	v_exp_f32_e32 v61, v61
	v_sub_f32_e32 v62, v62, v51
	v_add_f32_e32 v52, v58, v52
	v_exp_f32_e32 v62, v62
	v_sub_f32_e32 v63, v63, v51
	v_add_f32_e32 v52, v59, v52
	v_exp_f32_e32 v63, v63
	v_sub_f32_e32 v64, v64, v51
	v_add_f32_e32 v52, v60, v52
	v_exp_f32_e32 v64, v64
	v_sub_f32_e32 v65, v65, v51
	v_add_f32_e32 v52, v61, v52
	v_exp_f32_e32 v65, v65
	v_sub_f32_e32 v106, v110, v51
	v_add_f32_e32 v52, v62, v52
	v_exp_f32_e32 v106, v106
	v_sub_f32_e32 v50, v50, v51
	v_add_f32_e32 v52, v63, v52
	v_exp_f32_e32 v109, v50
	v_sub_f32_e32 v36, v36, v51
	v_add_f32_e32 v52, v64, v52
	v_exp_f32_e32 v36, v36
	v_sub_f32_e32 v37, v37, v51
	v_add_f32_e32 v52, v65, v52
	v_exp_f32_e32 v37, v37
	v_sub_f32_e32 v38, v38, v51
	v_add_f32_e32 v52, v106, v52
	v_exp_f32_e32 v110, v38
	v_sub_f32_e32 v39, v39, v51
	v_add_f32_e32 v50, v109, v52
	v_exp_f32_e32 v111, v39
	v_sub_f32_e32 v39, v40, v51
	v_add_f32_e32 v50, v36, v50
	v_exp_f32_e32 v112, v39
	v_sub_f32_e32 v39, v41, v51
	v_add_f32_e32 v50, v37, v50
	v_exp_f32_e32 v41, v39
	v_sub_f32_e32 v39, v42, v51
	v_add_f32_e32 v38, v110, v50
	v_exp_f32_e32 v113, v39
	v_sub_f32_e32 v39, v43, v51
	v_add_f32_e32 v38, v111, v38
	v_exp_f32_e32 v114, v39
	v_sub_f32_e32 v39, v44, v51
	v_add_f32_e32 v38, v112, v38
	v_exp_f32_e32 v115, v39
	v_sub_f32_e32 v39, v45, v51
	v_add_f32_e32 v38, v41, v38
	v_exp_f32_e32 v116, v39
	v_sub_f32_e32 v39, v46, v51
	v_add_f32_e32 v38, v113, v38
	v_exp_f32_e32 v117, v39
	v_sub_f32_e32 v39, v47, v51
	v_add_f32_e32 v38, v114, v38
	v_exp_f32_e32 v118, v39
	v_sub_f32_e32 v35, v35, v51
	v_add_f32_e32 v38, v115, v38
	v_exp_f32_e32 v119, v35
	v_sub_f32_e32 v34, v34, v51
	v_add_f32_e32 v38, v116, v38
	v_exp_f32_e32 v120, v34
	v_add_f32_e32 v38, v117, v38
	v_add_f32_e32 v38, v118, v38
	v_add_f32_e32 v35, v119, v38
	v_cvt_pk_bf16_f32 v47, v108, v53
	v_add_u32_e32 v53, s38, v104
	v_add_f32_e32 v34, v120, v35
	v_exp_f32_e32 v50, v48
	v_mov_b32_e32 v35, v202
	v_cvt_pk_bf16_f32 v44, v62, v63
	v_add_u32_e32 v62, 0x4800, v53
	v_cvt_pk_bf16_f32 v46, v49, v107
	v_cvt_pk_bf16_f32 v48, v54, v55
	v_cvt_pk_bf16_f32 v49, v56, v57
	v_cvt_pk_bf16_f32 v42, v58, v59
	v_cvt_pk_bf16_f32 v43, v60, v61
	v_pk_mul_f32 v[30:31], v[30:31], v[50:51] op_sel_hi:[1,0]
	v_pk_mul_f32 v[28:29], v[28:29], v[50:51] op_sel_hi:[1,0]
	v_pk_mul_f32 v[26:27], v[26:27], v[50:51] op_sel_hi:[1,0]
	v_pk_mul_f32 v[24:25], v[24:25], v[50:51] op_sel_hi:[1,0]
	v_pk_mul_f32 v[22:23], v[22:23], v[50:51] op_sel_hi:[1,0]
	v_pk_mul_f32 v[20:21], v[20:21], v[50:51] op_sel_hi:[1,0]
	v_pk_mul_f32 v[18:19], v[18:19], v[50:51] op_sel_hi:[1,0]
	v_pk_mul_f32 v[16:17], v[16:17], v[50:51] op_sel_hi:[1,0]
	v_cvt_pk_bf16_f32 v45, v64, v65
	v_cvt_pk_bf16_f32 v38, v106, v109
	s_waitcnt lgkmcnt(1)
	v_mfma_f32_32x32x16_bf16 v[16:31], v[180:183], v[46:49], v[16:31]
	v_cvt_pk_bf16_f32 v39, v36, v37
	v_cvt_pk_bf16_f32 v40, v110, v111
	v_cvt_pk_bf16_f32 v41, v112, v41
	v_lshlrev_b32_e32 v35, 2, v35
	v_bitop3_b32 v35, v35, s84, v211 bitop3:0x6c
	ds_bpermute_b32 v35, v35, v34
	s_waitcnt lgkmcnt(2)
	v_mfma_f32_32x32x16_bf16 v[16:31], v[184:187], v[42:45], v[16:31]
	v_cvt_pk_bf16_f32 v36, v117, v118
	v_cvt_pk_bf16_f32 v37, v119, v120
	v_add_u32_e32 v53, 0x5800, v53
	s_waitcnt lgkmcnt(0)
	v_add_f32_e32 v52, v34, v35
	v_cvt_pk_bf16_f32 v34, v113, v114
	v_cvt_pk_bf16_f32 v35, v115, v116
	v_pk_mul_f32 v[14:15], v[14:15], v[50:51] op_sel_hi:[1,0]
	v_mfma_f32_32x32x16_bf16 v[16:31], v[188:191], v[38:41], v[16:31]
	v_mul_f32_e64 v12, v12, v50
	v_mul_f32_e64 v13, v13, v50
	v_mul_f32_e64 v10, v10, v50
	v_mul_f32_e64 v11, v11, v50
	v_pk_mul_f32 v[8:9], v[8:9], v[50:51] op_sel_hi:[1,0]
	v_pk_mul_f32 v[6:7], v[6:7], v[50:51] op_sel_hi:[1,0]
	v_pk_mul_f32 v[4:5], v[4:5], v[50:51] op_sel_hi:[1,0]
	v_pk_mul_f32 v[2:3], v[2:3], v[50:51] op_sel_hi:[1,0]
	s_waitcnt lgkmcnt(0)
	v_mfma_f32_32x32x16_bf16 v[16:31], v[192:195], v[34:37], v[16:31]
	v_mul_f32_e64 v0, v0, v50
	v_mul_f32_e64 v1, v1, v50
	v_fmac_f32_e32 v52, v98, v50
	v_mov_b32_e32 v98, v52
	v_mov_b32_e32 v106, v51
	s_waitcnt lgkmcnt(0)
	v_mfma_f32_32x32x16_bf16 v[0:15], v[196:199], v[46:49], v[0:15]
	s_waitcnt lgkmcnt(0)
	v_mfma_f32_32x32x16_bf16 v[0:15], v[216:219], v[42:45], v[0:15]
	s_waitcnt lgkmcnt(0)
	v_mfma_f32_32x32x16_bf16 v[0:15], v[220:223], v[38:41], v[0:15]
	s_waitcnt lgkmcnt(0)
	v_mfma_f32_32x32x16_bf16 v[0:15], v[224:227], v[34:37], v[0:15]
